# attention prologue: shuffles/DMA issue no longer wait for Q loads; next unit Q tile L2-prefetched during last chunk
# baseline (speedup 1.0000x reference)
; __device__ __forceinline__ bool attn_unit(const Ptrs& P, LAS unsigned char* lds, int unit, int tid, int wave, int lane, bool pre, int nxt) {
;     ...
;     bf16_t* Qb = (bf16_t*)(ws + WS_Q) + (size_t)(b * SEQ + n * 128 + q0) * DM + h * 64;
;     const bf16_t* Kg = (const bf16_t*)(ws + WS_K) + (size_t)b * SEQ * KVW + kh * 64; const bf16_t* Vg = (const bf16_t*)(ws + WS_VT) + (size_t)(b * 4 + kh) * 64 * SEQ;
;     const bf16_t* Kcg = (const bf16_t*)(ws + WS_KC) + (size_t)b * CTX * KVW + kh * 64; const bf16_t* Vcg = (const bf16_t*)(ws + WS_VCT) + (size_t)(b * 4 + kh) * 64 * CTX;
;     float mq = fabsf(P.qg[lane]), mk = fabsf(P.kg[lane]);
; #pragma unroll
;     for (int o = 1; o < 64; o <<= 1) { mq = fmaxf(mq, __shfl_xor(mq, o)); mk = fmaxf(mk, __shfl_xor(mk, o)); }
;     const float sink2 = P.sink[h] * LOG2E; const float mshift = fmaxf(64.0f * QSCALE * mq * mk, sink2);
;     bf16x8_t qf[2][4];
; #pragma unroll
;     for (int cb = 0; cb < 2; ++cb)
; #pragma unroll
;         for (int ds = 0; ds < 4; ++ds) qf[cb][ds] = __builtin_nontemporal_load((const bf16x8_t*)(Qb + (size_t)(32 * cb + r) * DM + 16 * ds + 8 * hh));
;     f32x16 o[2][2];
; #pragma unroll
;     for (int db = 0; db < 2; ++db)
; #pragma unroll
;         for (int cb = 0; cb < 2; ++cb)
; #pragma unroll
;             for (int i = 0; i < 16; ++i) o[db][cb][i] = 0.f;
;     float rs[2] = {0.f, 0.f};
;     f32x16 negm;
; #pragma unroll
;     for (int i = 0; i < 16; ++i) negm[i] = -mshift;
;     ...
;     if (!pre) { if (n == 0) AT_DMA(1); else AT_DMA(0); }
.LBB9_308:
	global_load_dword v0, v[172:173], off
	global_load_dword v2, v[174:175], off
	s_and_b32 s43, s42, 31
	s_ashr_i32 s82, s42, 7
	s_lshl_b32 s47, s43, 7
	s_lshl_b32 s46, s82, 12
	s_add_i32 s70, s47, s33
	s_add_i32 s50, s70, s46
	s_bfe_u32 s44, s42, 0x20005
	s_mov_b32 s46, s50
	s_lshl_b32 s45, s44, 2
	s_ashr_i32 s83, s82, 31
	v_readlane_b32 s48, v251, 40
	s_ashr_i32 s51, s50, 31
	v_writelane_b32 v250, s46, 17
	s_or_b32 s45, s45, s48
	s_lshl_b64 s[48:49], s[82:83], 21
	v_writelane_b32 v250, s47, 18
	s_lshl_b64 s[78:79], s[50:51], 11
	v_readlane_b32 s46, v251, 59
	s_add_u32 s46, s46, s48
	v_readlane_b32 s48, v251, 60
	s_addc_u32 s48, s48, s49
	s_lshl_b32 s49, s44, 7
	s_add_u32 s96, s46, s49
	s_addc_u32 s97, s48, 0
	s_lshl_b32 s46, s82, 2
	s_or_b32 s70, s46, s44
	s_ashr_i32 s71, s70, 31
	s_lshl_b64 s[74:75], s[70:71], 19
	v_readlane_b32 s46, v251, 63
	s_add_u32 s46, s46, s78
	v_readlane_b32 s48, v250, 0
	s_addc_u32 s49, s48, s79
	s_lshl_b32 s48, s45, 7
	s_add_u32 s48, s46, s48
	s_addc_u32 s49, s49, 0
	s_mov_b64 s[88:89], s[72:73]
	s_mov_b64 s[80:81], s[34:35]
	s_mov_b64 s[34:35], s[30:31]
	s_mov_b64 s[30:31], s[28:29]
	s_mov_b64 s[28:29], s[26:27]
	s_mov_b64 s[26:27], s[24:25]
	s_mov_b64 s[24:25], s[22:23]
	s_mov_b64 s[22:23], s[20:21]
	s_mov_b64 s[20:21], s[18:19]
	s_mov_b64 s[18:19], s[16:17]
	s_mov_b64 s[16:17], s[14:15]
	s_mov_b64 s[14:15], s[12:13]
	s_mov_b64 s[12:13], s[10:11]
	s_mov_b64 s[10:11], s[8:9]
	s_mov_b64 s[8:9], s[6:7]
	s_mov_b64 s[6:7], s[4:5]
	s_mov_b64 s[4:5], s[0:1]
	s_mov_b64 s[0:1], s[66:67]
	s_mov_b64 s[40:41], s[64:65]
	s_mov_b64 s[66:67], s[62:63]
	s_mov_b64 s[64:65], s[60:61]
	s_mov_b64 s[72:73], s[56:57]
	s_lshl_b32 s46, s45, 2
	v_lshl_add_u64 v[4:5], s[48:49], 0, v[178:179]
	s_mov_b64 s[78:79], s[54:55]
	v_readlane_b32 s48, v251, 16
	v_mov_b32_e32 v3, s46
	v_readlane_b32 s56, v251, 24
	v_readlane_b32 s57, v251, 25
	v_lshl_add_u64 v[4:5], v[4:5], 0, v[180:181]
	v_readlane_b32 s51, v251, 19
	v_readlane_b32 s46, v250, 1
	v_readlane_b32 s50, v251, 18
	v_readlane_b32 s54, v251, 22
	global_load_dword v3, v3, s[56:57]
	s_nop 0
	global_load_dwordx4 v[114:117], v[4:5], off nt
	global_load_dwordx4 v[118:121], v[4:5], off offset:32 nt
	global_load_dwordx4 v[122:125], v[4:5], off offset:64 nt
	global_load_dwordx4 v[126:129], v[4:5], off offset:96 nt
	v_add_co_u32_e32 v4, vcc, 0x10000, v4
	v_readlane_b32 s55, v251, 23
	s_nop 0
	v_addc_co_u32_e32 v5, vcc, 0, v5, vcc
	global_load_dwordx4 v[130:133], v[4:5], off nt
	global_load_dwordx4 v[134:137], v[4:5], off offset:32 nt
	global_load_dwordx4 v[138:141], v[4:5], off offset:64 nt
	global_load_dwordx4 v[142:145], v[4:5], off offset:96 nt
	s_add_u32 s51, s46, s74
	s_waitcnt vmcnt(9)
	v_and_b32_e32 v4, 0x7fffffff, v0
	v_and_b32_e32 v5, 0x7fffffff, v2
	ds_bpermute_b32 v4, v185, v4
	ds_bpermute_b32 v5, v185, v5
	v_max_f32_e64 v0, |v0|, |v0|
	v_max_f32_e64 v2, |v2|, |v2|
	v_readlane_b32 s46, v250, 2
	s_waitcnt lgkmcnt(1)
	v_max_f32_e32 v4, v4, v4
	s_waitcnt lgkmcnt(0)
	v_max_f32_e32 v5, v5, v5
	v_max_f32_e32 v0, v0, v4
	v_max_f32_e32 v2, v2, v5
	ds_bpermute_b32 v4, v186, v0
	ds_bpermute_b32 v5, v186, v2
	s_mov_b64 s[54:55], s[78:79]
	v_readlane_b32 s50, v251, 32
	s_addc_u32 s46, s46, s75
	s_waitcnt lgkmcnt(1)
	v_max_f32_e32 v4, v4, v4
	s_waitcnt lgkmcnt(0)
	v_max_f32_e32 v5, v5, v5
	v_max_f32_e32 v0, v0, v4
	v_max_f32_e32 v2, v2, v5
	ds_bpermute_b32 v4, v187, v0
	ds_bpermute_b32 v5, v187, v2
	s_and_b64 vcc, exec, s[68:69]
	v_readlane_b32 s49, v251, 17
	v_readlane_b32 s52, v251, 20
	s_waitcnt lgkmcnt(1)
	v_max_f32_e32 v4, v4, v4
	s_waitcnt lgkmcnt(0)
	v_max_f32_e32 v5, v5, v5
	v_max_f32_e32 v0, v0, v4
	v_max_f32_e32 v2, v2, v5
	ds_bpermute_b32 v4, v188, v0
	ds_bpermute_b32 v5, v188, v2
	v_readlane_b32 s53, v251, 21
	v_readlane_b32 s58, v251, 26
	v_readlane_b32 s59, v251, 27
	s_waitcnt lgkmcnt(1)
	v_max_f32_e32 v4, v4, v4
	s_waitcnt lgkmcnt(0)
	v_max_f32_e32 v5, v5, v5
	v_max_f32_e32 v0, v0, v4
	v_max_f32_e32 v2, v2, v5
	ds_bpermute_b32 v4, v189, v0
	ds_bpermute_b32 v5, v189, v2
	v_readlane_b32 s60, v251, 28
	v_readlane_b32 s61, v251, 29
	v_readlane_b32 s62, v251, 30
	s_waitcnt lgkmcnt(1)
	v_max_f32_e32 v4, v4, v4
	s_waitcnt lgkmcnt(0)
	v_max_f32_e32 v5, v5, v5
	v_max_f32_e32 v9, v0, v4
	v_max_f32_e32 v8, v2, v5
	ds_bpermute_b32 v11, v190, v9
	ds_bpermute_b32 v10, v190, v8
	v_readlane_b32 s63, v251, 31
	s_cbranch_vccnz .LBB9_329
	s_cmp_lg_u32 s43, 0
	s_cbranch_scc0 .LBB9_319
	s_andn2_b64 vcc, exec, s[54:55]
	s_cbranch_vccnz .LBB9_318
	s_add_i32 s76, s43, -1
	s_lshl_b64 s[48:49], s[76:77], 16
	s_add_u32 s68, s96, s48
	s_addc_u32 s69, s97, s49
	s_lshl_b32 s48, s76, 8
	s_add_u32 s84, s51, s48
	s_addc_u32 s85, s46, 0
	v_mov_b32_e32 v12, v193
	v_mov_b32_e32 v2, v192
	s_mov_b32 s76, s50
	s_branch .LBB9_314

; #define AT_SYNC() do { asm volatile("s_waitcnt vmcnt(0) lgkmcnt(0)" ::: "memory"); __builtin_amdgcn_s_barrier(); asm volatile("" ::: "memory"); } while (0)
; __device__ __forceinline__ bool attn_unit(const Ptrs& P, LAS unsigned char* lds, int unit, int tid, int wave, int lane, bool pre, int nxt) {
;     ...
;     const float sink2 = P.sink[h] * LOG2E; const float mshift = fmaxf(64.0f * QSCALE * mq * mk, sink2);
;     bf16x8_t qf[2][4];
; #pragma unroll
;     for (int cb = 0; cb < 2; ++cb)
; #pragma unroll
;         for (int ds = 0; ds < 4; ++ds) qf[cb][ds] = __builtin_nontemporal_load((const bf16x8_t*)(Qb + (size_t)(32 * cb + r) * DM + 16 * ds + 8 * hh));
;     f32x16 o[2][2];
; #pragma unroll
;     for (int db = 0; db < 2; ++db)
; #pragma unroll
;         for (int cb = 0; cb < 2; ++cb)
; #pragma unroll
;             for (int i = 0; i < 16; ++i) o[db][cb][i] = 0.f;
;     float rs[2] = {0.f, 0.f};
;     f32x16 negm;
; #pragma unroll
;     for (int i = 0; i < 16; ++i) negm[i] = -mshift;
;     ...
;     if (!pre) { if (n == 0) AT_DMA(1); else AT_DMA(0); }
;     AT_SYNC();
;     const int n2 = nxt & 31; const bool pf = nxt >= 0 && n2 != 0;
.LBB9_329:
	s_waitcnt vmcnt(8) lgkmcnt(0)
	v_max_f32_e32 v0, v11, v11
	v_max_f32_e32 v2, v9, v9
	v_max_f32_e32 v0, v2, v0
	v_max_f32_e32 v2, v10, v10
	v_max_f32_e32 v4, v8, v8
	v_max_f32_e32 v2, v4, v2
	v_mul_f32_e32 v0, 0x4138aa3b, v0
	v_mul_f32_e32 v0, v2, v0
	v_mul_f32_e32 v177, 0x3fb8aa3b, v3
	v_max_f32_e32 v203, v0, v177
	s_waitcnt vmcnt(0) lgkmcnt(0)
	s_barrier
	v_xor_b32_e32 v18, 0x80000000, v203
	v_cndmask_b32_e64 v0, 0, 1, s[54:55]
	v_mov_b32_e32 v19, v18
	v_mov_b32_e32 v20, v18
	v_mov_b32_e32 v21, v18
	v_mov_b32_e32 v22, v18
	v_mov_b32_e32 v23, v18
	v_mov_b32_e32 v24, v18
	v_mov_b32_e32 v25, v18
	v_mov_b32_e32 v26, v18
	v_mov_b32_e32 v27, v18
	v_mov_b32_e32 v28, v18
	v_mov_b32_e32 v29, v18
	v_mov_b32_e32 v30, v18
	v_mov_b32_e32 v31, v18
	v_mov_b32_e32 v32, v18
	v_mov_b32_e32 v33, v18
	s_cmp_eq_u32 s43, 0
	v_cmp_ne_u32_e64 s[68:69], 1, v0
	s_cbranch_scc1 .LBB9_350
	s_mov_b64 s[56:57], s[72:73]
	s_mov_b64 s[72:73], s[88:89]
	v_readlane_b32 s88, v250, 9
	s_and_b64 vcc, exec, s[68:69]
	s_mov_b64 s[60:61], s[64:65]
	s_mov_b64 s[62:63], s[66:67]
	s_mov_b64 s[64:65], s[40:41]
	s_mov_b64 s[66:67], s[0:1]
	s_mov_b64 s[0:1], s[4:5]
	s_mov_b64 s[4:5], s[6:7]
	s_mov_b64 s[6:7], s[8:9]
	s_mov_b64 s[8:9], s[10:11]
	s_mov_b64 s[10:11], s[12:13]
	s_mov_b64 s[12:13], s[14:15]
	s_mov_b64 s[14:15], s[16:17]
	s_mov_b64 s[16:17], s[18:19]
	s_mov_b64 s[18:19], s[20:21]
	s_mov_b64 s[20:21], s[22:23]
	s_mov_b64 s[22:23], s[24:25]
	s_mov_b64 s[24:25], s[26:27]
	s_mov_b64 s[26:27], s[28:29]
	s_mov_b64 s[28:29], s[30:31]
	s_mov_b64 s[30:31], s[34:35]
	s_mov_b64 s[34:35], s[80:81]
	v_readlane_b32 s89, v250, 10
	v_readlane_b32 s90, v250, 11
	v_readlane_b32 s91, v250, 12
	v_readlane_b32 s92, v250, 13
	v_readlane_b32 s93, v250, 14
	v_readlane_b32 s94, v250, 15
	v_readlane_b32 s95, v250, 16
	s_cbranch_vccnz .LBB9_338
	s_lshl_b32 s48, s43, 16
	s_add_u32 s84, s96, s48
	s_addc_u32 s85, s97, 0
	s_lshl_b32 s47, s47, 1
	s_add_u32 s74, s51, s47
	s_addc_u32 s75, s46, 0
	v_mov_b32_e32 v3, v193
	v_mov_b32_e32 v2, v192
	s_mov_b32 s47, s50
	s_branch .LBB9_334

; __device__ __forceinline__ bool attn_unit(const Ptrs& P, LAS unsigned char* lds, int unit, int tid, int wave, int lane, bool pre, int nxt) {
;     ...
;     const int n2 = nxt & 31; const bool pf = nxt >= 0 && n2 != 0;
; #pragma unroll
;     for (int c = 0; c < 5; ++c) {
;         if (c == 0 && n == 0) continue;
;         if (c == 2 && n == 31) continue;
;     ...
;         for (int kt = 0; kt < 4; ++kt) {
;             if (c == 0 && 32 * kt + 31 < q0) continue;
;             if (c == 2 && 32 * kt > q0 + 63) continue;
;             bf16x8_t kf[4], vf[2][2];
; #pragma unroll
;             for (int ds = 0; ds < 4; ++ds) kf[ds] = *(const LAS bf16x8_t*)(Kl + (32 * kt + r) * AT_KP + (16 * ds + 8 * hh) * 2);
; #pragma unroll
;             for (int db = 0; db < 2; ++db)
; #pragma unroll
;                 for (int s = 0; s < 2; ++s) vf[db][s] = *(const LAS bf16x8_t*)(Vl + (32 * db + r) * AT_VP + (32 * kt + 16 * s + 8 * hh) * 2);
; #pragma unroll
;             for (int cb = 0; cb < 2; ++cb) {
;                 const int dq = 32 * kt - (q0 + 32 * cb);
;                 if ((c == 0 && dq < 0) || (c == 2 && dq > 0)) continue;
;                 const bool diag = (c == 0 || c == 2) && dq == 0;
;                 f32x16 st = MFMA32(kf[0], qf[cb][0], negm);
;                 st = MFMA32(kf[1], qf[cb][1], st); st = MFMA32(kf[2], qf[cb][2], st); st = MFMA32(kf[3], qf[cb][3], st);
;                 float p[16];
; #pragma unroll
;                 for (int i = 0; i < 16; ++i) p[i] = __builtin_amdgcn_exp2f(st[i]);
;                 if (diag) {
;                     const int thr = r - 4 * hh;
; #pragma unroll
;                     for (int i = 0; i < 16; ++i) { const bool vis = c == 0 ? crow(i, 0) >= thr : crow(i, 0) <= thr; p[i] = vis ? p[i] : 0.f; }
;                 }
;                 float s4 = 0.f;
; #pragma unroll
;                 for (int i = 0; i < 16; ++i) s4 += p[i];
;                 rs[cb] += s4;
; #pragma unroll
;                 for (int s = 0; s < 2; ++s) {
;                     u32x4 w; w.x = cvtpk(p[8 * s], p[8 * s + 1]); w.y = cvtpk(p[8 * s + 2], p[8 * s + 3]); w.z = cvtpk(p[8 * s + 4], p[8 * s + 5]); w.w = cvtpk(p[8 * s + 6], p[8 * s + 7]);
;                     const bf16x8_t pb = __builtin_bit_cast(bf16x8_t, w);
;                     o[0][cb] = MFMA32(vf[0][s], pb, o[0][cb]); o[1][cb] = MFMA32(vf[1][s], pb, o[1][cb]);
;                 }
;             }
;         }
.LBB9_400:
	s_waitcnt lgkmcnt(0)
	ds_read_b128 v[146:149], v0
	ds_read_b128 v[150:153], v0 offset:32
	v_add_u32_e32 v154, s43, v195
	v_add_u32_e32 v158, s43, v194
	s_add_i32 s43, s43, 64
	s_waitcnt lgkmcnt(0)
	v_mfma_f32_32x32x16_bf16 v[82:97], v[146:149], v[114:117], v[18:33]
	s_cmpk_lg_i32 s43, 0x100
	v_mfma_f32_32x32x16_bf16 v[98:113], v[146:149], v[130:133], v[18:33]
	v_mfma_f32_32x32x16_bf16 v[82:97], v[150:153], v[118:121], v[82:97]
	v_mfma_f32_32x32x16_bf16 v[98:113], v[150:153], v[134:137], v[98:113]
	ds_read_b128 v[146:149], v0 offset:64
	ds_read_b128 v[150:153], v0 offset:96
	v_add_u32_e32 v0, 0x1200, v0
	s_waitcnt lgkmcnt(0)
	v_mfma_f32_32x32x16_bf16 v[82:97], v[146:149], v[122:125], v[82:97]
	v_mfma_f32_32x32x16_bf16 v[98:113], v[146:149], v[138:141], v[98:113]
	ds_read_b128 v[146:149], v154
	ds_read_b128 v[154:157], v154 offset:32
	v_mfma_f32_32x32x16_bf16 v[82:97], v[150:153], v[126:129], v[82:97]
	v_mfma_f32_32x32x16_bf16 v[98:113], v[150:153], v[142:145], v[98:113]
	s_nop 10
	v_exp_f32_e32 v159, v89
	v_exp_f32_e32 v161, v87
	v_exp_f32_e32 v163, v85
	v_exp_f32_e32 v165, v83
	v_exp_f32_e32 v167, v82
	v_exp_f32_e32 v169, v84
	v_exp_f32_e32 v205, v86
	v_exp_f32_e32 v207, v88
	ds_read_b128 v[86:89], v158
	ds_read_b128 v[150:153], v158 offset:32
	v_exp_f32_e32 v166, v98
	v_exp_f32_e32 v164, v99
	v_exp_f32_e32 v168, v100
	v_exp_f32_e32 v162, v101
	v_exp_f32_e32 v204, v102
	v_exp_f32_e32 v160, v103
	v_exp_f32_e32 v206, v104
	v_exp_f32_e32 v158, v105
	v_cvt_pk_bf16_f32 v82, v167, v165
	v_cvt_pk_bf16_f32 v83, v169, v163
	v_cvt_pk_bf16_f32 v84, v205, v161
	v_cvt_pk_bf16_f32 v85, v207, v159
	v_pk_add_f32 v[102:103], v[166:167], 0 op_sel_hi:[1,0]
	v_exp_f32_e32 v97, v97
	s_waitcnt lgkmcnt(0)
	v_mfma_f32_32x32x16_bf16 v[66:81], v[146:149], v[82:85], v[66:81]
	v_add_f32_e64 v102, v164, v102
	v_add_f32_e64 v103, v165, v103
	v_exp_f32_e32 v99, v96
	v_pk_add_f32 v[102:103], v[168:169], v[102:103]
	v_exp_f32_e32 v95, v95
	v_exp_f32_e32 v93, v93
	v_exp_f32_e32 v91, v91
	v_exp_f32_e32 v101, v90
	v_mfma_f32_32x32x16_bf16 v[50:65], v[86:89], v[82:85], v[50:65]
	v_cvt_pk_bf16_f32 v82, v166, v164
	v_cvt_pk_bf16_f32 v83, v168, v162
	v_cvt_pk_bf16_f32 v84, v204, v160
	v_cvt_pk_bf16_f32 v85, v206, v158
	v_add_f32_e64 v102, v162, v102
	v_add_f32_e64 v103, v163, v103
	v_exp_f32_e32 v100, v106
	v_exp_f32_e32 v90, v107
	v_mfma_f32_32x32x16_bf16 v[34:49], v[146:149], v[82:85], v[34:49]
	v_exp_f32_e32 v98, v112
	v_exp_f32_e32 v96, v113
	v_pk_add_f32 v[102:103], v[204:205], v[102:103]
	s_nop 0
	v_pk_add_f32 v[102:103], v[160:161], v[102:103]
	s_nop 0
	v_pk_add_f32 v[102:103], v[206:207], v[102:103]
	v_mfma_f32_32x32x16_bf16 v[2:17], v[86:89], v[82:85], v[2:17]
	v_exp_f32_e32 v87, v92
	v_exp_f32_e32 v89, v94
	v_exp_f32_e32 v86, v108
	v_exp_f32_e32 v92, v109
	v_exp_f32_e32 v88, v110
	v_exp_f32_e32 v94, v111
	v_cvt_pk_bf16_f32 v82, v101, v91
	v_cvt_pk_bf16_f32 v83, v87, v93
	v_cvt_pk_bf16_f32 v84, v89, v95
	v_cvt_pk_bf16_f32 v85, v99, v97
	v_pk_add_f32 v[102:103], v[158:159], v[102:103]
	s_nop 0
	v_mfma_f32_32x32x16_bf16 v[66:81], v[154:157], v[82:85], v[66:81]
	v_mfma_f32_32x32x16_bf16 v[50:65], v[150:153], v[82:85], v[50:65]
	v_cvt_pk_bf16_f32 v82, v100, v90
	v_cvt_pk_bf16_f32 v83, v86, v92
	v_cvt_pk_bf16_f32 v84, v88, v94
	v_cvt_pk_bf16_f32 v85, v98, v96
	v_add_f32_e64 v100, v100, v102
	v_add_f32_e64 v101, v101, v103
	v_pk_add_f32 v[90:91], v[90:91], v[100:101]
	v_mfma_f32_32x32x16_bf16 v[34:49], v[154:157], v[82:85], v[34:49]
	v_mfma_f32_32x32x16_bf16 v[2:17], v[150:153], v[82:85], v[2:17]
	v_add_f32_e64 v82, v86, v90
	v_add_f32_e64 v83, v87, v91
	v_add_f32_e64 v82, v92, v82
	v_add_f32_e64 v83, v93, v83
	v_add_f32_e64 v82, v88, v82
	v_add_f32_e64 v83, v89, v83
	v_pk_add_f32 v[82:83], v[94:95], v[82:83]
	s_nop 0
	v_pk_add_f32 v[82:83], v[98:99], v[82:83]
	s_nop 0
	v_pk_add_f32 v[82:83], v[96:97], v[82:83]
	s_nop 0
	v_pk_add_f32 v[182:183], v[182:183], v[82:83]
	s_cbranch_scc1 .LBB9_400
	s_add_i32 s42, s42, s94
	s_cmpk_gt_i32 s42, 0x1ff
	s_cselect_b64 s[70:71], -1, 0
	s_cmpk_lt_i32 s42, 0x200
	s_cselect_b32 s43, s42, -1
	s_and_b32 s44, s43, 31
	s_cmp_gt_i32 s43, -1
	s_cselect_b64 s[46:47], -1, 0
	v_add_co_u32_e64 v0, s[48:49], s44, -1
	s_and_b64 s[68:69], s[46:47], s[48:49]
	s_waitcnt vmcnt(0) lgkmcnt(0)
	s_barrier
	s_cmp_lt_i32 s43, 0
	s_cbranch_scc1 .Lqpf_skip
	s_and_b32 s98, s43, 31
	s_lshl_b32 s98, s98, 7
	s_add_i32 s98, s98, s33
	s_ashr_i32 s99, s43, 7
	s_lshl_b32 s99, s99, 12
	s_add_i32 s98, s98, s99
	s_lshl_b32 s98, s98, 11
	s_bfe_u32 s99, s43, 0x20005
	s_lshl_b32 s99, s99, 2
	v_readlane_b32 vcc_lo, v251, 40
	s_nop 3
	s_or_b32 s99, s99, vcc_lo
	s_lshl_b32 s99, s99, 7
	s_add_u32 s98, s98, s99
	v_lshl_add_u32 v252, v170, 11, s98
	v_readlane_b32 s98, v251, 63
	v_readlane_b32 s99, v250, 0
	s_nop 7
	global_load_dword v252, v252, s[98:99]
.Lqpf_skip:
	s_and_b64 s[46:47], s[54:55], s[68:69]
	v_readfirstlane_b32 s74, v0
	s_andn2_b64 vcc, exec, s[46:47]
	s_cbranch_vccnz .LBB9_410
	s_lshr_b32 s76, s43, 7
	s_lshl_b64 s[46:47], s[76:77], 21
	v_readlane_b32 s40, v251, 59
	s_add_u32 s44, s40, s46
	v_readlane_b32 s40, v251, 60
	s_addc_u32 s46, s40, s47
	s_lshl_b32 s43, s43, 1
	s_and_b32 s43, s43, 0xc0
	s_lshl_b32 s47, s43, 1
	s_add_u32 s44, s44, s47
	s_mov_b32 s75, s77
	s_addc_u32 s48, s46, 0
	s_lshl_b64 s[46:47], s[74:75], 16
	s_add_u32 s82, s44, s46
	s_addc_u32 s83, s48, s47
	s_lshl_b32 s44, s76, 8
	s_or_b32 s76, s44, s43
	s_lshl_b64 s[46:47], s[76:77], 13
	v_readlane_b32 s40, v250, 1
	s_add_u32 s43, s40, s46
	v_readlane_b32 s40, v250, 2
	s_addc_u32 s44, s40, s47
	s_lshl_b32 s46, s74, 8
	s_add_u32 s74, s43, s46
	s_addc_u32 s75, s44, 0
	v_mov_b32_e32 v83, v193
	v_mov_b32_e32 v82, v192
	s_mov_b32 s43, s50
	s_branch .LBB9_405

; #define LAS __attribute__((address_space(3)))
; __global__ void __launch_bounds__(NTHR, 2) mk_fwd(MkArgs a) {
;     extern __shared__ __attribute__((aligned(16))) unsigned char lds_raw[];
;     LAS unsigned char* lds = (LAS unsigned char*)lds_raw;
;     cg::grid_group grid = cg::this_grid();
;     const Ptrs& P = a.P;
;     const int tid = threadIdx.x, lane = tid & 63, wave = __builtin_amdgcn_readfirstlane(tid >> 6), bx = blockIdx.x, G = gridDim.x;
	.amdhsa_kernel _Z6mk_fwd6MkArgs
		.amdhsa_group_segment_fixed_size 0
		.amdhsa_private_segment_fixed_size 0
		.amdhsa_kernarg_size 440
		.amdhsa_user_sgpr_count 2
		.amdhsa_user_sgpr_dispatch_ptr 0
		.amdhsa_user_sgpr_queue_ptr 0
		.amdhsa_user_sgpr_kernarg_segment_ptr 1
		.amdhsa_user_sgpr_dispatch_id 0
		.amdhsa_user_sgpr_kernarg_preload_length 0
		.amdhsa_user_sgpr_kernarg_preload_offset 0
		.amdhsa_user_sgpr_private_segment_size 0
		.amdhsa_uses_dynamic_stack 0
		.amdhsa_enable_private_segment 0
		.amdhsa_system_sgpr_workgroup_id_x 1
		.amdhsa_system_sgpr_workgroup_id_y 0
		.amdhsa_system_sgpr_workgroup_id_z 0
		.amdhsa_system_sgpr_workgroup_info 0
		.amdhsa_system_vgpr_workitem_id 2
		.amdhsa_next_free_vgpr 256
		.amdhsa_next_free_sgpr 100
		.amdhsa_accum_offset 256
		.amdhsa_reserve_vcc 1
		.amdhsa_float_round_mode_32 0
		.amdhsa_float_round_mode_16_64 0
		.amdhsa_float_denorm_mode_32 3
		.amdhsa_float_denorm_mode_16_64 3
		.amdhsa_dx10_clamp 1
		.amdhsa_ieee_mode 1
		.amdhsa_fp16_overflow 0
		.amdhsa_tg_split 0
		.amdhsa_exception_fp_ieee_invalid_op 0
		.amdhsa_exception_fp_denorm_src 0
		.amdhsa_exception_fp_ieee_div_zero 0
		.amdhsa_exception_fp_ieee_overflow 0
		.amdhsa_exception_fp_ieee_underflow 0
		.amdhsa_exception_fp_ieee_inexact 0
		.amdhsa_exception_int_div_zero 0
	.end_amdhsa_kernel

; __device__ __forceinline__ unsigned f2bf(float f) { unsigned u = __float_as_uint(f); return (u + 0x7fffu + ((u >> 16) & 1u)) >> 16; }
; __device__ __forceinline__ float siluf_(float v) { return v * __builtin_amdgcn_rcpf(1.0f + __builtin_amdgcn_exp2f(-LOG2E * v)); }
; __global__ void k_transpose(const float* W, int K, int N, bf16_t* WT, int upmode) {
;     const size_t total = (size_t)K * N;
;     for (size_t idx = (size_t)blockIdx.x * blockDim.x + threadIdx.x; idx < total; idx += (size_t)gridDim.x * blockDim.x) {
;         const int np = (int)(idx / K), k = (int)(idx % K); const int n = upmode ? up_src_col(np) : np;
;         WT[idx] = (bf16_t)f2bf(W[(size_t)k * N + n]);
;     }
; }
; __global__ void k_mod(Ptrs P) {
;     const int idx = blockIdx.x * blockDim.x + threadIdx.x; if (idx >= 5 * NMOD) return;
;     const int r = idx / NMOD, n = idx % NMOD; const float* cv = r < 4 ? P.c + (size_t)r * DM : P.c_ctx; float s = 0.f;
;     for (int k = 0; k < DM; ++k) s += siluf_(cv[k]) * P.mod_w[(size_t)k * NMOD + n];
;     ((float*)(P.ws + WS_MOD))[idx] = s + P.mod_b[n];
; }
; __global__ void k_rows(Ptrs P) {
;     const int gw = (blockIdx.x * blockDim.x + threadIdx.x) >> 6, nw = (gridDim.x * blockDim.x) >> 6, lane = threadIdx.x & 63;
;     const float* mod = (const float*)(P.ws + WS_MOD); bf16_t* H = (bf16_t*)(P.ws + WS_H);
;     for (int m = gw; m < MTOK + MCTX; m += nw) {
;         const float* xr = m < MTOK ? P.x + (size_t)m * DM : P.ctx + (size_t)(m - MTOK) * DM; const float* mb = mod + (size_t)(m < MTOK ? (m >> 12) : 4) * NMOD;
;         h_row(xr, P.n1g, mb, mb + DM, H + (size_t)m * DM, lane);
;     }
;     for (int np = gw; np < NUP; np += nw) bias2_row((const bf16_t*)(P.ws + WS_WUP) + (size_t)np * DM, mod, (float*)(P.ws + WS_B2), np, lane);
; }
amdhsa.kernels:
  - .agpr_count:     0
    .args:
      - .address_space:  global
        .offset:         0
        .size:           8
        .value_kind:     global_buffer
      - .offset:         8
        .size:           4
        .value_kind:     by_value
      - .offset:         12
        .size:           4
        .value_kind:     by_value
      - .address_space:  global
        .offset:         16
        .size:           8
        .value_kind:     global_buffer
      - .offset:         24
        .size:           4
        .value_kind:     by_value
      - .offset:         32
        .size:           4
        .value_kind:     hidden_block_count_x
      - .offset:         36
        .size:           4
        .value_kind:     hidden_block_count_y
      - .offset:         40
        .size:           4
        .value_kind:     hidden_block_count_z
      - .offset:         44
        .size:           2
        .value_kind:     hidden_group_size_x
      - .offset:         46
        .size:           2
        .value_kind:     hidden_group_size_y
      - .offset:         48
        .size:           2
        .value_kind:     hidden_group_size_z
      - .offset:         50
        .size:           2
        .value_kind:     hidden_remainder_x
      - .offset:         52
        .size:           2
        .value_kind:     hidden_remainder_y
      - .offset:         54
        .size:           2
        .value_kind:     hidden_remainder_z
      - .offset:         72
        .size:           8
        .value_kind:     hidden_global_offset_x
      - .offset:         80
        .size:           8
        .value_kind:     hidden_global_offset_y
      - .offset:         88
        .size:           8
        .value_kind:     hidden_global_offset_z
      - .offset:         96
        .size:           2
        .value_kind:     hidden_grid_dims
    .group_segment_fixed_size: 0
    .kernarg_segment_align: 8
    .kernarg_segment_size: 288
    .language:       OpenCL C
    .language_version:
      - 2
      - 0
    .max_flat_workgroup_size: 1024
    .name:           _Z11k_transposePKfiiPti
    .private_segment_fixed_size: 0
    .sgpr_count:     36
    .sgpr_spill_count: 0
    .symbol:         _Z11k_transposePKfiiPti.kd
    .uniform_work_group_size: 1
    .uses_dynamic_stack: false
    .vgpr_count:     17
    .vgpr_spill_count: 0
    .wavefront_size: 64
  - .agpr_count:     0
    .args:
      - .offset:         0
        .size:           176
        .value_kind:     by_value
      - .offset:         176
        .size:           4
        .value_kind:     hidden_block_count_x
      - .offset:         180
        .size:           4
        .value_kind:     hidden_block_count_y
      - .offset:         184
        .size:           4
        .value_kind:     hidden_block_count_z
      - .offset:         188
        .size:           2
        .value_kind:     hidden_group_size_x
      - .offset:         190
        .size:           2
        .value_kind:     hidden_group_size_y
      - .offset:         192
        .size:           2
        .value_kind:     hidden_group_size_z
      - .offset:         194
        .size:           2
        .value_kind:     hidden_remainder_x
      - .offset:         196
        .size:           2
        .value_kind:     hidden_remainder_y
      - .offset:         198
        .size:           2
        .value_kind:     hidden_remainder_z
      - .offset:         216
        .size:           8
        .value_kind:     hidden_global_offset_x
      - .offset:         224
        .size:           8
        .value_kind:     hidden_global_offset_y
      - .offset:         232
        .size:           8
        .value_kind:     hidden_global_offset_z
      - .offset:         240
        .size:           2
        .value_kind:     hidden_grid_dims
    .group_segment_fixed_size: 0
    .kernarg_segment_align: 8
    .kernarg_segment_size: 432
    .language:       OpenCL C
    .language_version:
      - 2
      - 0
    .max_flat_workgroup_size: 1024
    .name:           _Z5k_mod4Ptrs
    .private_segment_fixed_size: 0
    .sgpr_count:     18
    .sgpr_spill_count: 0
    .symbol:         _Z5k_mod4Ptrs.kd
    .uniform_work_group_size: 1
    .uses_dynamic_stack: false
    .vgpr_count:     20
    .vgpr_spill_count: 0
    .wavefront_size: 64
  - .agpr_count:     0
    .args:
      - .offset:         0
        .size:           176
        .value_kind:     by_value
      - .offset:         176
        .size:           4
        .value_kind:     hidden_block_count_x
      - .offset:         180
        .size:           4
        .value_kind:     hidden_block_count_y
      - .offset:         184
        .size:           4
        .value_kind:     hidden_block_count_z
      - .offset:         188
        .size:           2
        .value_kind:     hidden_group_size_x
      - .offset:         190
        .size:           2
        .value_kind:     hidden_group_size_y
      - .offset:         192
        .size:           2
        .value_kind:     hidden_group_size_z
      - .offset:         194
        .size:           2
        .value_kind:     hidden_remainder_x
      - .offset:         196
        .size:           2
        .value_kind:     hidden_remainder_y
      - .offset:         198
        .size:           2
        .value_kind:     hidden_remainder_z
      - .offset:         216
        .size:           8
        .value_kind:     hidden_global_offset_x
      - .offset:         224
        .size:           8
        .value_kind:     hidden_global_offset_y
      - .offset:         232
        .size:           8
        .value_kind:     hidden_global_offset_z
      - .offset:         240
        .size:           2
        .value_kind:     hidden_grid_dims
    .group_segment_fixed_size: 0
    .kernarg_segment_align: 8
    .kernarg_segment_size: 432
    .language:       OpenCL C
    .language_version:
      - 2
      - 0
    .max_flat_workgroup_size: 1024
    .name:           _Z6k_rows4Ptrs
    .private_segment_fixed_size: 0
    .sgpr_count:     30
    .sgpr_spill_count: 0
    .symbol:         _Z6k_rows4Ptrs.kd
    .uniform_work_group_size: 1
    .uses_dynamic_stack: false
    .vgpr_count:     70
    .vgpr_spill_count: 0
    .wavefront_size: 64
; __global__ void k_gemm_out(const bf16_t* A, const bf16_t* Bt, EpiOut E) {
;     const int gw = (blockIdx.x * blockDim.x + threadIdx.x) >> 6, lane = threadIdx.x & 63, nrb = MTOK / 64;
;     if (gw >= nrb * (DM / 8)) return;
;     const int row = (gw % nrb) * 64 + lane, c0 = (gw / nrb) * 8;
;     float acc[8];
; #pragma unroll
;     for (int j = 0; j < 8; ++j) acc[j] = 0.f;
;     for (int k0 = 0; k0 < DM; k0 += 8) {
;         float a[8]; unpack8(*(const u32x4*)(A + (size_t)row * DM + k0), a);
; #pragma unroll
;         for (int j = 0; j < 8; ++j) { float b[8]; unpack8(*(const u32x4*)(Bt + (size_t)(c0 + j) * DM + k0), b);
; #pragma unroll
;             for (int i = 0; i < 8; ++i) acc[j] += a[i] * b[i]; }
;     }
;     (void)E(row, c0, acc);
; }
; __global__ void k_ssq(const float* out, float* SSQ) {
;     const int idx = blockIdx.x * blockDim.x + threadIdx.x; if (idx >= MTOK * 4) return;
;     const float* p = out + (size_t)(idx >> 2) * DM + (idx & 3) * 256; float s = 0.f;
;     for (int i = 0; i < 256; ++i) s += p[i] * p[i];
;     SSQ[idx] = s;
; }
; __global__ void k_gemm_up(const bf16_t* A, const bf16_t* Bt, const float* SSQ, EpiUp E) {
;     const int gw = (blockIdx.x * blockDim.x + threadIdx.x) >> 6, lane = threadIdx.x & 63, nrb = MTOK / 64;
;     if (gw >= nrb * (FF / 8)) return;
;     const int row = (gw % nrb) * 64 + lane, c0 = (gw / nrb) * 8, np = ((c0 >> 7) << 8) + (c0 & 127);
;     float aa[8], ab[8];
; #pragma unroll
;     for (int j = 0; j < 8; ++j) { aa[j] = 0.f; ab[j] = 0.f; }
;     for (int k0 = 0; k0 < DM; k0 += 8) {
;         float a[8]; unpack8(*(const u32x4*)(A + (size_t)row * DM + k0), a);
; #pragma unroll
;         for (int j = 0; j < 8; ++j) { float b[8]; unpack8(*(const u32x4*)(Bt + (size_t)(np + j) * DM + k0), b);
; #pragma unroll
;             for (int i = 0; i < 8; ++i) aa[j] += a[i] * b[i];
;             unpack8(*(const u32x4*)(Bt + (size_t)(np + 128 + j) * DM + k0), b);
; #pragma unroll
;             for (int i = 0; i < 8; ++i) ab[j] += a[i] * b[i]; }
;     }
;     E(row, c0, row_rstd(SSQ, row), aa, ab);
; }
  - .agpr_count:     0
    .args:
      - .address_space:  global
        .offset:         0
        .size:           8
        .value_kind:     global_buffer
      - .address_space:  global
        .offset:         8
        .size:           8
        .value_kind:     global_buffer
      - .offset:         16
        .size:           40
        .value_kind:     by_value
      - .offset:         56
        .size:           4
        .value_kind:     hidden_block_count_x
      - .offset:         60
        .size:           4
        .value_kind:     hidden_block_count_y
      - .offset:         64
        .size:           4
        .value_kind:     hidden_block_count_z
      - .offset:         68
        .size:           2
        .value_kind:     hidden_group_size_x
      - .offset:         70
        .size:           2
        .value_kind:     hidden_group_size_y
      - .offset:         72
        .size:           2
        .value_kind:     hidden_group_size_z
      - .offset:         74
        .size:           2
        .value_kind:     hidden_remainder_x
      - .offset:         76
        .size:           2
        .value_kind:     hidden_remainder_y
      - .offset:         78
        .size:           2
        .value_kind:     hidden_remainder_z
      - .offset:         96
        .size:           8
        .value_kind:     hidden_global_offset_x
      - .offset:         104
        .size:           8
        .value_kind:     hidden_global_offset_y
      - .offset:         112
        .size:           8
        .value_kind:     hidden_global_offset_z
      - .offset:         120
        .size:           2
        .value_kind:     hidden_grid_dims
    .group_segment_fixed_size: 0
    .kernarg_segment_align: 8
    .kernarg_segment_size: 312
    .language:       OpenCL C
    .language_version:
      - 2
      - 0
    .max_flat_workgroup_size: 1024
    .name:           _Z10k_gemm_outPKtS0_6EpiOut
    .private_segment_fixed_size: 0
    .sgpr_count:     26
    .sgpr_spill_count: 0
    .symbol:         _Z10k_gemm_outPKtS0_6EpiOut.kd
    .uniform_work_group_size: 1
    .uses_dynamic_stack: false
    .vgpr_count:     100
    .vgpr_spill_count: 0
    .wavefront_size: 64
  - .agpr_count:     0
    .args:
      - .address_space:  global
        .offset:         0
        .size:           8
        .value_kind:     global_buffer
      - .address_space:  global
        .offset:         8
        .size:           8
        .value_kind:     global_buffer
      - .offset:         16
        .size:           4
        .value_kind:     hidden_block_count_x
      - .offset:         20
        .size:           4
        .value_kind:     hidden_block_count_y
      - .offset:         24
        .size:           4
        .value_kind:     hidden_block_count_z
      - .offset:         28
        .size:           2
        .value_kind:     hidden_group_size_x
      - .offset:         30
        .size:           2
        .value_kind:     hidden_group_size_y
      - .offset:         32
        .size:           2
        .value_kind:     hidden_group_size_z
      - .offset:         34
        .size:           2
        .value_kind:     hidden_remainder_x
      - .offset:         36
        .size:           2
        .value_kind:     hidden_remainder_y
      - .offset:         38
        .size:           2
        .value_kind:     hidden_remainder_z
      - .offset:         56
        .size:           8
        .value_kind:     hidden_global_offset_x
      - .offset:         64
        .size:           8
        .value_kind:     hidden_global_offset_y
      - .offset:         72
        .size:           8
        .value_kind:     hidden_global_offset_z
      - .offset:         80
        .size:           2
        .value_kind:     hidden_grid_dims
    .group_segment_fixed_size: 0
    .kernarg_segment_align: 8
    .kernarg_segment_size: 272
    .language:       OpenCL C
    .language_version:
      - 2
      - 0
    .max_flat_workgroup_size: 1024
    .name:           _Z5k_ssqPKfPf
    .private_segment_fixed_size: 0
    .sgpr_count:     10
    .sgpr_spill_count: 0
    .symbol:         _Z5k_ssqPKfPf.kd
    .uniform_work_group_size: 1
    .uses_dynamic_stack: false
    .vgpr_count:     24
    .vgpr_spill_count: 0
    .wavefront_size: 64
  - .agpr_count:     0
    .args:
      - .address_space:  global
        .offset:         0
        .size:           8
        .value_kind:     global_buffer
      - .address_space:  global
        .offset:         8
        .size:           8
        .value_kind:     global_buffer
      - .address_space:  global
        .offset:         16
        .size:           8
        .value_kind:     global_buffer
      - .offset:         24
        .size:           16
        .value_kind:     by_value
      - .offset:         40
        .size:           4
        .value_kind:     hidden_block_count_x
      - .offset:         44
        .size:           4
        .value_kind:     hidden_block_count_y
      - .offset:         48
        .size:           4
        .value_kind:     hidden_block_count_z
      - .offset:         52
        .size:           2
        .value_kind:     hidden_group_size_x
      - .offset:         54
        .size:           2
        .value_kind:     hidden_group_size_y
      - .offset:         56
        .size:           2
        .value_kind:     hidden_group_size_z
      - .offset:         58
        .size:           2
        .value_kind:     hidden_remainder_x
      - .offset:         60
        .size:           2
        .value_kind:     hidden_remainder_y
      - .offset:         62
        .size:           2
        .value_kind:     hidden_remainder_z
      - .offset:         80
        .size:           8
        .value_kind:     hidden_global_offset_x
      - .offset:         88
        .size:           8
        .value_kind:     hidden_global_offset_y
      - .offset:         96
        .size:           8
        .value_kind:     hidden_global_offset_z
      - .offset:         104
        .size:           2
        .value_kind:     hidden_grid_dims
    .group_segment_fixed_size: 0
    .kernarg_segment_align: 8
    .kernarg_segment_size: 296
    .language:       OpenCL C
    .language_version:
      - 2
      - 0
    .max_flat_workgroup_size: 1024
    .name:           _Z9k_gemm_upPKtS0_PKf5EpiUp
    .private_segment_fixed_size: 0
    .sgpr_count:     22
    .sgpr_spill_count: 0
    .symbol:         _Z9k_gemm_upPKtS0_PKf5EpiUp.kd
    .uniform_work_group_size: 1
    .uses_dynamic_stack: false
    .vgpr_count:     68
    .vgpr_spill_count: 0
    .wavefront_size: 64
; __global__ void __launch_bounds__(256) k_qk(Ptrs P, int ctxmode) {
;     const int gw = (blockIdx.x * blockDim.x + threadIdx.x) >> 6, lane = threadIdx.x & 63;
;     const int nrows = ctxmode ? MCTX : MTOK, nrb = nrows / 64, nheads = ctxmode ? 4 : 20;
;     if (gw >= nrb * nheads) return;
;     const int row = (gw % nrb) * 64 + lane, hh = gw / nrb;
;     const bool isq = !ctxmode && hh < 16; const int wtile = (ctxmode || hh >= 16) ? 4 : hh >> 2, whd = hh & 3;
;     const bf16_t* A = (const bf16_t*)(P.ws + WS_H) + (size_t)(ctxmode ? MTOK + row : row) * DM; const bf16_t* Bt = (const bf16_t*)(P.ws + WS_WIN);
;     float acc[64];
; #pragma unroll
;     for (int j = 0; j < 64; ++j) acc[j] = 0.f;
;     for (int k0 = 0; k0 < DM; k0 += 8) {
;         float a[8]; unpack8(*(const u32x4*)(A + k0), a);
; #pragma unroll
;         for (int j = 0; j < 64; ++j) { float b[8]; unpack8(*(const u32x4*)(Bt + (size_t)qk_row(wtile, whd, j) * DM + k0), b);
; #pragma unroll
;             for (int i = 0; i < 8; ++i) acc[j] += a[i] * b[i]; }
;     }
;     float ss = 0.f;
; #pragma unroll
;     for (int j = 0; j < 64; ++j) ss += acc[j] * acc[j];
;     const float rstd = 1.0f / sqrtf(ss * (1.0f / 64.0f) + EPS); const float* g = isq ? P.qg : P.kg;
; #pragma unroll
;     for (int j = 0; j < 64; ++j) acc[j] = acc[j] * rstd * g[j];
;     bf16_t* dst;
;     if (ctxmode) dst = (bf16_t*)(P.ws + WS_KC) + (size_t)row * KVW + hh * 64;
;     else {
;         const int t = row & 4095;
; #pragma unroll
;         for (int a = 0; a < 2; ++a) { const float pos = (float)(a ? (t & 63) : (t >> 6));
; #pragma unroll
;             for (int f = 0; f < 16; ++f) { const float ang = pos * exp2f(-(float)f * (13.287712379549449f / 16.0f)); float sn, cs; sincosf(ang, &sn, &cs);
;                 const float x1 = acc[32 * a + f], x2 = acc[32 * a + 16 + f]; acc[32 * a + f] = x1 * cs - x2 * sn; acc[32 * a + 16 + f] = x2 * cs + x1 * sn; } }
;         if (isq) {
; #pragma unroll
;             for (int j = 0; j < 64; ++j) acc[j] *= QSCALE;
;             dst = (bf16_t*)(P.ws + WS_Q) + (size_t)row * DM + hh * 64;
;         } else dst = (bf16_t*)(P.ws + WS_K) + (size_t)row * KVW + (hh - 16) * 64;
;     }
; #pragma unroll
;     for (int j = 0; j < 64; j += 8) { float o[8];
; #pragma unroll
;         for (int i = 0; i < 8; ++i) o[i] = acc[j + i];
;         *(u32x4*)(dst + j) = pack8(o); }
; }
  - .agpr_count:     0
    .args:
      - .offset:         0
        .size:           176
        .value_kind:     by_value
      - .offset:         176
        .size:           4
        .value_kind:     by_value
      - .offset:         184
        .size:           4
        .value_kind:     hidden_block_count_x
      - .offset:         188
        .size:           4
        .value_kind:     hidden_block_count_y
      - .offset:         192
        .size:           4
        .value_kind:     hidden_block_count_z
      - .offset:         196
        .size:           2
        .value_kind:     hidden_group_size_x
      - .offset:         198
        .size:           2
        .value_kind:     hidden_group_size_y
      - .offset:         200
        .size:           2
        .value_kind:     hidden_group_size_z
      - .offset:         202
        .size:           2
        .value_kind:     hidden_remainder_x
      - .offset:         204
        .size:           2
        .value_kind:     hidden_remainder_y
      - .offset:         206
        .size:           2
        .value_kind:     hidden_remainder_z
      - .offset:         224
        .size:           8
        .value_kind:     hidden_global_offset_x
      - .offset:         232
        .size:           8
        .value_kind:     hidden_global_offset_y
      - .offset:         240
        .size:           8
        .value_kind:     hidden_global_offset_z
      - .offset:         248
        .size:           2
        .value_kind:     hidden_grid_dims
    .group_segment_fixed_size: 0
    .kernarg_segment_align: 8
    .kernarg_segment_size: 440
    .language:       OpenCL C
    .language_version:
      - 2
      - 0
    .max_flat_workgroup_size: 256
    .name:           _Z4k_qk4Ptrsi
    .private_segment_fixed_size: 0
    .sgpr_count:     37
    .sgpr_spill_count: 0
    .symbol:         _Z4k_qk4Ptrsi.kd
    .uniform_work_group_size: 1
    .uses_dynamic_stack: false
    .vgpr_count:     214
    .vgpr_spill_count: 0
    .wavefront_size: 64
  - .agpr_count:     0
    .args:
      - .offset:         0
        .size:           176
        .value_kind:     by_value
      - .offset:         176
        .size:           4
        .value_kind:     hidden_block_count_x
      - .offset:         180
        .size:           4
        .value_kind:     hidden_block_count_y
      - .offset:         184
        .size:           4
        .value_kind:     hidden_block_count_z
      - .offset:         188
        .size:           2
        .value_kind:     hidden_group_size_x
      - .offset:         190
        .size:           2
        .value_kind:     hidden_group_size_y
      - .offset:         192
        .size:           2
        .value_kind:     hidden_group_size_z
      - .offset:         194
        .size:           2
        .value_kind:     hidden_remainder_x
      - .offset:         196
        .size:           2
        .value_kind:     hidden_remainder_y
      - .offset:         198
        .size:           2
        .value_kind:     hidden_remainder_z
      - .offset:         216
        .size:           8
        .value_kind:     hidden_global_offset_x
      - .offset:         224
        .size:           8
        .value_kind:     hidden_global_offset_y
      - .offset:         232
        .size:           8
        .value_kind:     hidden_global_offset_z
      - .offset:         240
        .size:           2
        .value_kind:     hidden_grid_dims
    .group_segment_fixed_size: 0
    .kernarg_segment_align: 8
    .kernarg_segment_size: 432
    .language:       OpenCL C
    .language_version:
      - 2
      - 0
    .max_flat_workgroup_size: 256
    .name:           _Z6k_attn4Ptrs
    .private_segment_fixed_size: 0
    .sgpr_count:     23
    .sgpr_spill_count: 0
    .symbol:         _Z6k_attn4Ptrs.kd
    .uniform_work_group_size: 1
    .uses_dynamic_stack: false
    .vgpr_count:     254
    .vgpr_spill_count: 0
    .wavefront_size: 64
  - .agpr_count:     0
    .args:
      - .address_space:  global
        .offset:         0
        .size:           8
        .value_kind:     global_buffer
      - .address_space:  global
        .offset:         8
        .size:           8
        .value_kind:     global_buffer
      - .offset:         16
        .size:           4
        .value_kind:     hidden_block_count_x
      - .offset:         20
        .size:           4
        .value_kind:     hidden_block_count_y
      - .offset:         24
        .size:           4
        .value_kind:     hidden_block_count_z
      - .offset:         28
        .size:           2
        .value_kind:     hidden_group_size_x
      - .offset:         30
        .size:           2
        .value_kind:     hidden_group_size_y
      - .offset:         32
        .size:           2
        .value_kind:     hidden_group_size_z
      - .offset:         34
        .size:           2
        .value_kind:     hidden_remainder_x
      - .offset:         36
        .size:           2
        .value_kind:     hidden_remainder_y
      - .offset:         38
        .size:           2
        .value_kind:     hidden_remainder_z
      - .offset:         56
        .size:           8
        .value_kind:     hidden_global_offset_x
      - .offset:         64
        .size:           8
        .value_kind:     hidden_global_offset_y
      - .offset:         72
        .size:           8
        .value_kind:     hidden_global_offset_z
      - .offset:         80
        .size:           2
        .value_kind:     hidden_grid_dims
    .group_segment_fixed_size: 0
    .kernarg_segment_align: 8
    .kernarg_segment_size: 272
    .language:       OpenCL C
    .language_version:
      - 2
      - 0
    .max_flat_workgroup_size: 1024
    .name:           _Z6k_diffPKtPt
    .private_segment_fixed_size: 0
    .sgpr_count:     16
    .sgpr_spill_count: 0
    .symbol:         _Z6k_diffPKtPt.kd
    .uniform_work_group_size: 1
    .uses_dynamic_stack: false
    .vgpr_count:     10
    .vgpr_spill_count: 0
    .wavefront_size: 64
; __device__ __forceinline__ unsigned f2bf(float f) { unsigned u = __float_as_uint(f); return (u + 0x7fffu + ((u >> 16) & 1u)) >> 16; }
; __device__ __forceinline__ u32x4 pack8(const float (&v)[8]) { u32x4 w; w.x = cvtpk(v[0], v[1]); w.y = cvtpk(v[2], v[3]); w.z = cvtpk(v[4], v[5]); w.w = cvtpk(v[6], v[7]); return w; }
; __device__ __forceinline__ float sigmoidf_(float v) { return __builtin_amdgcn_rcpf(1.0f + __builtin_amdgcn_exp2f(-LOG2E * v)); }
; #define LAS __attribute__((address_space(3)))
;     __device__ __forceinline__ void operator()(int row, int c0, const float (&v)[8]) const {
;         if (c0 < 1536) {
;             const int b = row >> 12, t = row & 4095, cv = c0 - 1280, kh = cv >> 6, d0 = cv & 63;
;             bf16_t* p = Vt + ((size_t)((b * 4 + kh) * 64 + d0)) * SEQ + perm16(t);
; #pragma unroll
;             for (int i = 0; i < 8; ++i) p[(size_t)i * SEQ] = (bf16_t)f2bf(v[i]);
;         } else if (c0 < 2048) {
;             *(u32x4*)(POOLIN + (size_t)row * POOLW + (c0 - 1536)) = pack8(v);
;         } else {
;             const int s = c0 - 2048, gc = ((s >> 7) & 1) * 1024 + ((s >> 8) << 7) + (s & 127); float g[8];
; #pragma unroll
;             for (int i = 0; i < 8; ++i) g[i] = sigmoidf_(v[i] + gate_b[gc + i]);
;             *(u32x4*)(GATES + (size_t)row * 2048 + gc) = pack8(g);
;         }
;     }
; __global__ void __launch_bounds__(NTHR, 2) mk_fwd(MkArgs a) {
;     extern __shared__ __attribute__((aligned(16))) unsigned char lds_raw[];
;     LAS unsigned char* lds = (LAS unsigned char*)lds_raw;
;     cg::grid_group grid = cg::this_grid();
;     const Ptrs& P = a.P;
;     const int tid = threadIdx.x, lane = tid & 63, wave = __builtin_amdgcn_readfirstlane(tid >> 6), bx = blockIdx.x, G = gridDim.x;
;     const int lo = a.ph_lo, hi = a.ph_hi;
;     ...
;     volatile LAS unsigned* bst = (volatile LAS unsigned*)(lds + 147456);
;     if (tid < 2) bst[tid] = 0u;
;     if (((MK_MASK_ >> 2) & 1) && a.ph_lo <= 2 && 2 < a.ph_hi) {
;         for (int i = tid; i < 1024; i += NTHR) { const int pos = i >> 4, f = i & 15; const float ang = (float)pos * exp2f(-(float)f * (13.287712379549449f / 16.0f));
;             ((LAS float*)(lds + RING_BYTES))[2048 + i] = cosf(ang); ((LAS float*)(lds + RING_BYTES))[3072 + i] = sinf(ang); }
;     }
;     __syncthreads();
;     const XcdBarrier xbar = xcd_barrier_post((unsigned*)P.ws, bst);
;     if (lo < 0) grid.sync();
  - .agpr_count:     0
    .args:
      - .offset:         0
        .size:           184
        .value_kind:     by_value
      - .offset:         184
        .size:           4
        .value_kind:     hidden_block_count_x
      - .offset:         188
        .size:           4
        .value_kind:     hidden_block_count_y
      - .offset:         192
        .size:           4
        .value_kind:     hidden_block_count_z
      - .offset:         196
        .size:           2
        .value_kind:     hidden_group_size_x
      - .offset:         198
        .size:           2
        .value_kind:     hidden_group_size_y
      - .offset:         200
        .size:           2
        .value_kind:     hidden_group_size_z
      - .offset:         202
        .size:           2
        .value_kind:     hidden_remainder_x
      - .offset:         204
        .size:           2
        .value_kind:     hidden_remainder_y
      - .offset:         206
        .size:           2
        .value_kind:     hidden_remainder_z
      - .offset:         224
        .size:           8
        .value_kind:     hidden_global_offset_x
      - .offset:         232
        .size:           8
        .value_kind:     hidden_global_offset_y
      - .offset:         240
        .size:           8
        .value_kind:     hidden_global_offset_z
      - .offset:         248
        .size:           2
        .value_kind:     hidden_grid_dims
      - .offset:         272
        .size:           8
        .value_kind:     hidden_multigrid_sync_arg
      - .offset:         304
        .size:           4
        .value_kind:     hidden_dynamic_lds_size
    .group_segment_fixed_size: 0
    .kernarg_segment_align: 8
    .kernarg_segment_size: 440
    .language:       OpenCL C
    .language_version:
      - 2
      - 0
    .max_flat_workgroup_size: 512
    .name:           _Z6mk_fwd6MkArgs
    .private_segment_fixed_size: 0
    .sgpr_count:     106
    .sgpr_spill_count: 83
    .symbol:         _Z6mk_fwd6MkArgs.kd
    .uniform_work_group_size: 1
    .uses_dynamic_stack: false
    .vgpr_count:     256
    .vgpr_spill_count: 0
    .wavefront_size: 64
  - .agpr_count:     0
    .args:
      - .address_space:  global
        .offset:         0
        .size:           8
        .value_kind:     global_buffer
      - .offset:         8
        .size:           4
        .value_kind:     by_value
      - .address_space:  global
        .offset:         16
        .size:           8
        .value_kind:     global_buffer
      - .offset:         24
        .size:           4
        .value_kind:     by_value
      - .offset:         28
        .size:           4
        .value_kind:     by_value
      - .offset:         32
        .size:           4
        .value_kind:     by_value
      - .offset:         36
        .size:           4
        .value_kind:     by_value
      - .offset:         40
        .size:           4
        .value_kind:     by_value
      - .offset:         48
        .size:           32
        .value_kind:     by_value
      - .offset:         80
        .size:           4
        .value_kind:     hidden_block_count_x
      - .offset:         84
        .size:           4
        .value_kind:     hidden_block_count_y
      - .offset:         88
        .size:           4
        .value_kind:     hidden_block_count_z
      - .offset:         92
        .size:           2
        .value_kind:     hidden_group_size_x
      - .offset:         94
        .size:           2
        .value_kind:     hidden_group_size_y
      - .offset:         96
        .size:           2
        .value_kind:     hidden_group_size_z
      - .offset:         98
        .size:           2
        .value_kind:     hidden_remainder_x
      - .offset:         100
        .size:           2
        .value_kind:     hidden_remainder_y
      - .offset:         102
        .size:           2
        .value_kind:     hidden_remainder_z
      - .offset:         120
        .size:           8
        .value_kind:     hidden_global_offset_x
      - .offset:         128
        .size:           8
        .value_kind:     hidden_global_offset_y
      - .offset:         136
        .size:           8
        .value_kind:     hidden_global_offset_z
      - .offset:         144
        .size:           2
        .value_kind:     hidden_grid_dims
    .group_segment_fixed_size: 0
    .kernarg_segment_align: 8
    .kernarg_segment_size: 336
    .language:       OpenCL C
    .language_version:
      - 2
      - 0
    .max_flat_workgroup_size: 1024
    .name:           _Z6k_gemmI9EpiInRestEvPKtiS2_iiiiiT_
    .private_segment_fixed_size: 0
    .sgpr_count:     21
    .sgpr_spill_count: 0
    .symbol:         _Z6k_gemmI9EpiInRestEvPKtiS2_iiiiiT_.kd
    .uniform_work_group_size: 1
    .uses_dynamic_stack: false
    .vgpr_count:     98
    .vgpr_spill_count: 0
    .wavefront_size: 64
; __device__ __forceinline__ unsigned f2bf(float f) { unsigned u = __float_as_uint(f); return (u + 0x7fffu + ((u >> 16) & 1u)) >> 16; }
; __device__ __forceinline__ u32x4 pack8(const float (&v)[8]) { u32x4 w; w.x = cvtpk(v[0], v[1]); w.y = cvtpk(v[2], v[3]); w.z = cvtpk(v[4], v[5]); w.w = cvtpk(v[6], v[7]); return w; }
; __device__ __forceinline__ int perm16(int t) { return (t & ~12) | ((t & 4) << 1) | ((t & 8) >> 1); }
;     __device__ __forceinline__ void operator()(int row, int c0, const float (&v)[8]) const {
;         const int b = row >> 8, t = row & 255, kh = c0 >> 6, d0 = c0 & 63;
;         bf16_t* p = Vct + ((size_t)((b * 4 + kh) * 64 + d0)) * CTX + perm16(t);
; #pragma unroll
;         for (int i = 0; i < 8; ++i) p[(size_t)i * CTX] = (bf16_t)f2bf(v[i]);
;     }
;     __device__ __forceinline__ void operator()(int row, int c0, const float (&v)[8]) const {
;         float o[8];
; #pragma unroll
;         for (int i = 0; i < 8; ++i) o[i] = v[i] * pool_scale[g * 128 + c0 + i];
;         *(u32x4*)(PM + (size_t)row * PMP + g * 128 + c0) = pack8(o);
;     }
; template <class Epi> __global__ void k_gemm(const bf16_t* A, int lda, const bf16_t* Bt, int ldb, int Mrows, int N, int K, int col_off, Epi E) {
;     const int gw = (blockIdx.x * blockDim.x + threadIdx.x) >> 6, lane = threadIdx.x & 63, nrb = Mrows / 64;
;     if (gw >= nrb * (N / 8)) return;
;     const int row = (gw % nrb) * 64 + lane, c0 = (gw / nrb) * 8;
;     float acc[8];
; #pragma unroll
;     for (int j = 0; j < 8; ++j) acc[j] = 0.f;
;     for (int k0 = 0; k0 < K; k0 += 8) {
;         float a[8]; unpack8(*(const u32x4*)(A + (size_t)row * lda + k0), a);
; #pragma unroll
;         for (int j = 0; j < 8; ++j) { float b[8]; unpack8(*(const u32x4*)(Bt + (size_t)(c0 + j) * ldb + k0), b);
; #pragma unroll
;             for (int i = 0; i < 8; ++i) acc[j] += a[i] * b[i]; }
;     }
;     E(row, c0 + col_off, acc);
; }
  - .agpr_count:     0
    .args:
      - .address_space:  global
        .offset:         0
        .size:           8
        .value_kind:     global_buffer
      - .offset:         8
        .size:           4
        .value_kind:     by_value
      - .address_space:  global
        .offset:         16
        .size:           8
        .value_kind:     global_buffer
      - .offset:         24
        .size:           4
        .value_kind:     by_value
      - .offset:         28
        .size:           4
        .value_kind:     by_value
      - .offset:         32
        .size:           4
        .value_kind:     by_value
      - .offset:         36
        .size:           4
        .value_kind:     by_value
      - .offset:         40
        .size:           4
        .value_kind:     by_value
      - .address_space:  global
        .offset:         48
        .size:           8
        .value_kind:     global_buffer
      - .offset:         56
        .size:           4
        .value_kind:     hidden_block_count_x
      - .offset:         60
        .size:           4
        .value_kind:     hidden_block_count_y
      - .offset:         64
        .size:           4
        .value_kind:     hidden_block_count_z
      - .offset:         68
        .size:           2
        .value_kind:     hidden_group_size_x
      - .offset:         70
        .size:           2
        .value_kind:     hidden_group_size_y
      - .offset:         72
        .size:           2
        .value_kind:     hidden_group_size_z
      - .offset:         74
        .size:           2
        .value_kind:     hidden_remainder_x
      - .offset:         76
        .size:           2
        .value_kind:     hidden_remainder_y
      - .offset:         78
        .size:           2
        .value_kind:     hidden_remainder_z
      - .offset:         96
        .size:           8
        .value_kind:     hidden_global_offset_x
      - .offset:         104
        .size:           8
        .value_kind:     hidden_global_offset_y
      - .offset:         112
        .size:           8
        .value_kind:     hidden_global_offset_z
      - .offset:         120
        .size:           2
        .value_kind:     hidden_grid_dims
    .group_segment_fixed_size: 0
    .kernarg_segment_align: 8
    .kernarg_segment_size: 312
    .language:       OpenCL C
    .language_version:
      - 2
      - 0
    .max_flat_workgroup_size: 1024
    .name:           _Z6k_gemmI7EpiCtxVEvPKtiS2_iiiiiT_
    .private_segment_fixed_size: 0
    .sgpr_count:     21
    .sgpr_spill_count: 0
    .symbol:         _Z6k_gemmI7EpiCtxVEvPKtiS2_iiiiiT_.kd
    .uniform_work_group_size: 1
    .uses_dynamic_stack: false
    .vgpr_count:     98
    .vgpr_spill_count: 0
    .wavefront_size: 64
  - .agpr_count:     0
    .args:
      - .address_space:  global
        .offset:         0
        .size:           8
        .value_kind:     global_buffer
      - .offset:         8
        .size:           4
        .value_kind:     by_value
      - .address_space:  global
        .offset:         16
        .size:           8
        .value_kind:     global_buffer
      - .offset:         24
        .size:           4
        .value_kind:     by_value
      - .offset:         28
        .size:           4
        .value_kind:     by_value
      - .offset:         32
        .size:           4
        .value_kind:     by_value
      - .offset:         36
        .size:           4
        .value_kind:     by_value
      - .offset:         40
        .size:           4
        .value_kind:     by_value
      - .offset:         48
        .size:           24
        .value_kind:     by_value
      - .offset:         72
        .size:           4
        .value_kind:     hidden_block_count_x
      - .offset:         76
        .size:           4
        .value_kind:     hidden_block_count_y
      - .offset:         80
        .size:           4
        .value_kind:     hidden_block_count_z
      - .offset:         84
        .size:           2
        .value_kind:     hidden_group_size_x
      - .offset:         86
        .size:           2
        .value_kind:     hidden_group_size_y
      - .offset:         88
        .size:           2
        .value_kind:     hidden_group_size_z
      - .offset:         90
        .size:           2
        .value_kind:     hidden_remainder_x
      - .offset:         92
        .size:           2
        .value_kind:     hidden_remainder_y
      - .offset:         94
        .size:           2
        .value_kind:     hidden_remainder_z
      - .offset:         112
        .size:           8
        .value_kind:     hidden_global_offset_x
      - .offset:         120
        .size:           8
        .value_kind:     hidden_global_offset_y
      - .offset:         128
        .size:           8
        .value_kind:     hidden_global_offset_z
      - .offset:         136
        .size:           2
        .value_kind:     hidden_grid_dims
    .group_segment_fixed_size: 0
    .kernarg_segment_align: 8
    .kernarg_segment_size: 328
    .language:       OpenCL C
    .language_version:
      - 2
      - 0
    .max_flat_workgroup_size: 1024
    .name:           _Z6k_gemmI10EpiPoolMixEvPKtiS2_iiiiiT_
    .private_segment_fixed_size: 0
    .sgpr_count:     21
    .sgpr_spill_count: 0
    .symbol:         _Z6k_gemmI10EpiPoolMixEvPKtiS2_iiiiiT_.kd
    .uniform_work_group_size: 1
    .uses_dynamic_stack: false
    .vgpr_count:     96
    .vgpr_spill_count: 0
    .wavefront_size: 64
; __device__ __forceinline__ u32x4 pack8(const float (&v)[8]) { u32x4 w; w.x = cvtpk(v[0], v[1]); w.y = cvtpk(v[2], v[3]); w.z = cvtpk(v[4], v[5]); w.w = cvtpk(v[6], v[7]); return w; }
;     __device__ __forceinline__ void operator()(int row, int c0, const float (&v)[8]) const {
;         float g[8], o[8]; unpack8(*(const u32x4*)(GATES + (size_t)row * 2048 + 1024 + c0), g);
; #pragma unroll
;         for (int i = 0; i < 8; ++i) o[i] = g[i] * v[i];
;         *(u32x4*)(PG + (size_t)row * DM + c0) = pack8(o);
;     }
; template <class Epi> __global__ void k_gemm(const bf16_t* A, int lda, const bf16_t* Bt, int ldb, int Mrows, int N, int K, int col_off, Epi E) {
;     const int gw = (blockIdx.x * blockDim.x + threadIdx.x) >> 6, lane = threadIdx.x & 63, nrb = Mrows / 64;
;     if (gw >= nrb * (N / 8)) return;
;     const int row = (gw % nrb) * 64 + lane, c0 = (gw / nrb) * 8;
;     float acc[8];
; #pragma unroll
;     for (int j = 0; j < 8; ++j) acc[j] = 0.f;
;     for (int k0 = 0; k0 < K; k0 += 8) {
;         float a[8]; unpack8(*(const u32x4*)(A + (size_t)row * lda + k0), a);
; #pragma unroll
;         for (int j = 0; j < 8; ++j) { float b[8]; unpack8(*(const u32x4*)(Bt + (size_t)(c0 + j) * ldb + k0), b);
; #pragma unroll
;             for (int i = 0; i < 8; ++i) acc[j] += a[i] * b[i]; }
;     }
;     E(row, c0 + col_off, acc);
; }
  - .agpr_count:     0
    .args:
      - .address_space:  global
        .offset:         0
        .size:           8
        .value_kind:     global_buffer
      - .offset:         8
        .size:           4
        .value_kind:     by_value
      - .address_space:  global
        .offset:         16
        .size:           8
        .value_kind:     global_buffer
      - .offset:         24
        .size:           4
        .value_kind:     by_value
      - .offset:         28
        .size:           4
        .value_kind:     by_value
      - .offset:         32
        .size:           4
        .value_kind:     by_value
      - .offset:         36
        .size:           4
        .value_kind:     by_value
      - .offset:         40
        .size:           4
        .value_kind:     by_value
      - .offset:         48
        .size:           16
        .value_kind:     by_value
      - .offset:         64
        .size:           4
        .value_kind:     hidden_block_count_x
      - .offset:         68
        .size:           4
        .value_kind:     hidden_block_count_y
      - .offset:         72
        .size:           4
        .value_kind:     hidden_block_count_z
      - .offset:         76
        .size:           2
        .value_kind:     hidden_group_size_x
      - .offset:         78
        .size:           2
        .value_kind:     hidden_group_size_y
      - .offset:         80
        .size:           2
        .value_kind:     hidden_group_size_z
      - .offset:         82
        .size:           2
        .value_kind:     hidden_remainder_x
      - .offset:         84
        .size:           2
        .value_kind:     hidden_remainder_y
      - .offset:         86
        .size:           2
        .value_kind:     hidden_remainder_z
      - .offset:         104
        .size:           8
        .value_kind:     hidden_global_offset_x
      - .offset:         112
        .size:           8
        .value_kind:     hidden_global_offset_y
      - .offset:         120
        .size:           8
        .value_kind:     hidden_global_offset_z
      - .offset:         128
        .size:           2
        .value_kind:     hidden_grid_dims
    .group_segment_fixed_size: 0
    .kernarg_segment_align: 8
    .kernarg_segment_size: 320
    .language:       OpenCL C
    .language_version:
      - 2
      - 0
    .max_flat_workgroup_size: 1024
    .name:           _Z6k_gemmI11EpiPoolProjEvPKtiS2_iiiiiT_
    .private_segment_fixed_size: 0
    .sgpr_count:     21
    .sgpr_spill_count: 0
    .symbol:         _Z6k_gemmI11EpiPoolProjEvPKtiS2_iiiiiT_.kd
    .uniform_work_group_size: 1
    .uses_dynamic_stack: false
    .vgpr_count:     96
    .vgpr_spill_count: 0
    .wavefront_size: 64
;     __device__ __forceinline__ void operator()(int row, int c0, const float (&v)[8]) const {
;         float g[8], p[8], o[8]; unpack8(*(const u32x4*)(GATES + (size_t)row * 2048 + c0), g); unpack8(*(const u32x4*)(PG + (size_t)row * DM + c0), p);
; #pragma unroll
;         for (int i = 0; i < 8; ++i) o[i] = g[i] * v[i] + p[i];
;         *(u32x4*)(PG + (size_t)row * DM + c0) = pack8(o);
;     }
;     __device__ __forceinline__ float operator()(int row, int c0, const float (&v)[8]) const {
;         const int b = row >> 12; const float* mb = mod + (size_t)b * NMOD; float o[8], y[8], ss = 0.f;
; #pragma unroll
;         for (int h = 0; h < 2; ++h) {
;             const f32x4 xv = *(const f32x4*)(x + (size_t)row * DM + c0 + 4 * h), g1 = *(const f32x4*)(mb + 2 * DM + c0 + 4 * h), sc2 = *(const f32x4*)(mb + 4 * DM + c0 + 4 * h), ng = *(const f32x4*)(n2g + c0 + 4 * h);
; #pragma unroll
;             for (int i = 0; i < 4; ++i) { const float x1 = xv[i] + g1[i] * v[4 * h + i]; o[4 * h + i] = x1; ss += x1 * x1; y[4 * h + i] = x1 * (ng[i] * (1.0f + sc2[i])); }
;             *(f32x4*)(out + (size_t)row * DM + c0 + 4 * h) = (f32x4){o[4 * h], o[4 * h + 1], o[4 * h + 2], o[4 * h + 3]};
;         }
;         *(u32x4*)(Y2 + (size_t)row * DM + c0) = pack8(y);
;         return ss;
;     }
;     __device__ __forceinline__ void operator()(int row, int c0, float rstd, const float (&va)[8], const float (&vb)[8]) const {
;         const int b = row >> 12, np = ((c0 >> 7) << 8) + (c0 & 127); const float* bb = bias2 + (size_t)b * NUP + np; float o[8];
; #pragma unroll
; template <class Epi> __global__ void k_gemm(const bf16_t* A, int lda, const bf16_t* Bt, int ldb, int Mrows, int N, int K, int col_off, Epi E) {
;     const int gw = (blockIdx.x * blockDim.x + threadIdx.x) >> 6, lane = threadIdx.x & 63, nrb = Mrows / 64;
;     if (gw >= nrb * (N / 8)) return;
;     const int row = (gw % nrb) * 64 + lane, c0 = (gw / nrb) * 8;
;     float acc[8];
; #pragma unroll
;     for (int j = 0; j < 8; ++j) acc[j] = 0.f;
;     for (int k0 = 0; k0 < K; k0 += 8) {
;         float a[8]; unpack8(*(const u32x4*)(A + (size_t)row * lda + k0), a);
; #pragma unroll
;         for (int j = 0; j < 8; ++j) { float b[8]; unpack8(*(const u32x4*)(Bt + (size_t)(c0 + j) * ldb + k0), b);
; #pragma unroll
;             for (int i = 0; i < 8; ++i) acc[j] += a[i] * b[i]; }
;     }
;     E(row, c0 + col_off, acc);
; }
  - .agpr_count:     0
    .args:
      - .address_space:  global
        .offset:         0
        .size:           8
        .value_kind:     global_buffer
      - .offset:         8
        .size:           4
        .value_kind:     by_value
      - .address_space:  global
        .offset:         16
        .size:           8
        .value_kind:     global_buffer
      - .offset:         24
        .size:           4
        .value_kind:     by_value
      - .offset:         28
        .size:           4
        .value_kind:     by_value
      - .offset:         32
        .size:           4
        .value_kind:     by_value
      - .offset:         36
        .size:           4
        .value_kind:     by_value
      - .offset:         40
        .size:           4
        .value_kind:     by_value
      - .offset:         48
        .size:           16
        .value_kind:     by_value
      - .offset:         64
        .size:           4
        .value_kind:     hidden_block_count_x
      - .offset:         68
        .size:           4
        .value_kind:     hidden_block_count_y
      - .offset:         72
        .size:           4
        .value_kind:     hidden_block_count_z
      - .offset:         76
        .size:           2
        .value_kind:     hidden_group_size_x
      - .offset:         78
        .size:           2
        .value_kind:     hidden_group_size_y
      - .offset:         80
        .size:           2
        .value_kind:     hidden_group_size_z
      - .offset:         82
        .size:           2
        .value_kind:     hidden_remainder_x
      - .offset:         84
        .size:           2
        .value_kind:     hidden_remainder_y
      - .offset:         86
        .size:           2
        .value_kind:     hidden_remainder_z
      - .offset:         104
        .size:           8
        .value_kind:     hidden_global_offset_x
      - .offset:         112
        .size:           8
        .value_kind:     hidden_global_offset_y
      - .offset:         120
        .size:           8
        .value_kind:     hidden_global_offset_z
      - .offset:         128
        .size:           2
        .value_kind:     hidden_grid_dims
    .group_segment_fixed_size: 0
    .kernarg_segment_align: 8
    .kernarg_segment_size: 320
    .language:       OpenCL C
    .language_version:
      - 2
      - 0
    .max_flat_workgroup_size: 1024
    .name:           _Z6k_gemmI11EpiAttnProjEvPKtiS2_iiiiiT_
    .private_segment_fixed_size: 0
    .sgpr_count:     21
    .sgpr_spill_count: 0
    .symbol:         _Z6k_gemmI11EpiAttnProjEvPKtiS2_iiiiiT_.kd
    .uniform_work_group_size: 1
    .uses_dynamic_stack: false
    .vgpr_count:     96
    .vgpr_spill_count: 0
    .wavefront_size: 64
  - .agpr_count:     0
    .args:
      - .address_space:  global
        .offset:         0
        .size:           8
        .value_kind:     global_buffer
      - .offset:         8
        .size:           4
        .value_kind:     by_value
      - .address_space:  global
        .offset:         16
        .size:           8
        .value_kind:     global_buffer
      - .offset:         24
        .size:           4
        .value_kind:     by_value
      - .offset:         28
        .size:           4
        .value_kind:     by_value
      - .offset:         32
        .size:           4
        .value_kind:     by_value
      - .offset:         36
        .size:           4
        .value_kind:     by_value
      - .offset:         40
        .size:           4
        .value_kind:     by_value
      - .offset:         48
        .size:           24
        .value_kind:     by_value
      - .offset:         72
        .size:           4
        .value_kind:     hidden_block_count_x
      - .offset:         76
        .size:           4
        .value_kind:     hidden_block_count_y
      - .offset:         80
        .size:           4
        .value_kind:     hidden_block_count_z
      - .offset:         84
        .size:           2
        .value_kind:     hidden_group_size_x
      - .offset:         86
        .size:           2
        .value_kind:     hidden_group_size_y
      - .offset:         88
        .size:           2
        .value_kind:     hidden_group_size_z
      - .offset:         90
        .size:           2
        .value_kind:     hidden_remainder_x
      - .offset:         92
        .size:           2
        .value_kind:     hidden_remainder_y
      - .offset:         94
        .size:           2
        .value_kind:     hidden_remainder_z
      - .offset:         112
        .size:           8
        .value_kind:     hidden_global_offset_x
      - .offset:         120
        .size:           8
        .value_kind:     hidden_global_offset_y
      - .offset:         128
        .size:           8
        .value_kind:     hidden_global_offset_z
      - .offset:         136
        .size:           2
        .value_kind:     hidden_grid_dims
    .group_segment_fixed_size: 0
    .kernarg_segment_align: 8
    .kernarg_segment_size: 328
    .language:       OpenCL C
    .language_version:
      - 2
      - 0
    .max_flat_workgroup_size: 1024
    .name:           _Z6k_gemmI7EpiDownEvPKtiS2_iiiiiT_
    .private_segment_fixed_size: 0
    .sgpr_count:     25
    .sgpr_spill_count: 0
    .symbol:         _Z6k_gemmI7EpiDownEvPKtiS2_iiiiiT_.kd
    .uniform_work_group_size: 1
    .uses_dynamic_stack: false
    .vgpr_count:     96
    .vgpr_spill_count: 0
    .wavefront_size: 64
